# combo + 128x128 in-proj tile store loop rewritten
# speedup vs baseline: 1.0009x; 1.0009x over previous
; template <int NTW>
; DI void inproj_tile(const Params& p, int l, int mt, int ntile, char* lds) {
;     ...
; #pragma unroll 4
;   for (int i = 0; i < NCOLS / 16; ++i) {
;     const int c = tid + 256 * i, tl = c / (NCOLS / 8), ch = c % (NCOLS / 8);
;     const u32x4 v = *(const u32x4*)(lds + tl * RS + ch * 16);
;     *(u32x4*)(proj + ((size_t)mt * 128 + tl) * NP + ntile * NCOLS + ch * 8) = v;
;   }
.LBB0_224:
	v_lshrrev_b32_e32 v4, 4, v86
	v_and_b32_e32 v5, 15, v86
	v_lshlrev_b32_e32 v5, 4, v5
	v_mad_u32_u24 v6, v4, s75, v5
	v_mad_u32_u24 v7, v4, s33, v5
	s_mul_i32 s4, s80, s33
	s_add_u32 s4, s0, s4
	s_addc_u32 s5, s1, 0
	ds_read_b128 v[12:15], v6
	ds_read_b128 v[16:19], v6 offset:4352
	ds_read_b128 v[20:23], v6 offset:8704
	ds_read_b128 v[24:27], v6 offset:13056
	ds_read_b128 v[28:31], v6 offset:17408
	ds_read_b128 v[32:35], v6 offset:21760
	ds_read_b128 v[36:39], v6 offset:26112
	ds_read_b128 v[40:43], v6 offset:30464
	s_waitcnt lgkmcnt(7)
	global_store_dwordx4 v7, v[12:15], s[4:5]
	s_add_u32 s4, s4, 0x1a000
	s_addc_u32 s5, s5, 0
	s_waitcnt lgkmcnt(6)
	global_store_dwordx4 v7, v[16:19], s[4:5]
	s_add_u32 s4, s4, 0x1a000
	s_addc_u32 s5, s5, 0
	s_waitcnt lgkmcnt(5)
	global_store_dwordx4 v7, v[20:23], s[4:5]
	s_add_u32 s4, s4, 0x1a000
	s_addc_u32 s5, s5, 0
	s_waitcnt lgkmcnt(4)
	global_store_dwordx4 v7, v[24:27], s[4:5]
	s_add_u32 s4, s4, 0x1a000
	s_addc_u32 s5, s5, 0
	s_waitcnt lgkmcnt(3)
	global_store_dwordx4 v7, v[28:31], s[4:5]
	s_add_u32 s4, s4, 0x1a000
	s_addc_u32 s5, s5, 0
	s_waitcnt lgkmcnt(2)
	global_store_dwordx4 v7, v[32:35], s[4:5]
	s_add_u32 s4, s4, 0x1a000
	s_addc_u32 s5, s5, 0
	s_waitcnt lgkmcnt(1)
	global_store_dwordx4 v7, v[36:39], s[4:5]
	s_add_u32 s4, s4, 0x1a000
	s_addc_u32 s5, s5, 0
	s_waitcnt lgkmcnt(0)
	global_store_dwordx4 v7, v[40:43], s[4:5]
